# group-sync poll loops without the s_sleep between polls (tighter polling cadence)
# speedup vs baseline: 1.0139x; 1.0139x over previous
; __device__ __forceinline__ unsigned xb_ld(unsigned* p)              { return __hip_atomic_load(p, __ATOMIC_RELAXED, __HIP_MEMORY_SCOPE_AGENT); }
; __device__ __forceinline__ unsigned xb_add(unsigned* p, unsigned v) { return __hip_atomic_fetch_add(p, v, __ATOMIC_RELAXED, __HIP_MEMORY_SCOPE_AGENT); }
; #define XB_SPIN(cond, bar) do { unsigned _sp = 0; while (cond) { __builtin_amdgcn_s_sleep(1); \
;     if ((++_sp & 255u) == 0u) { if (xb_ld(&(bar)[XB_TMO])) break; if (_sp > XB_SPIN_CAP) { atomicAdd(&(bar)[XB_TMO], 1u); break; } } } } while (0)
; #define SEAM(k) do { if (IN(k) && IN((k) + 1)) GRID_SYNC(); } while (0)
; __device__ __forceinline__ void xcd_barrier(const XcdBarrier& b) {
;     asm volatile("s_waitcnt vmcnt(0)" ::: "memory");
;     __syncthreads();
;     if (threadIdx.x == 0) {
;         unsigned* bar = b.bar;
;         __builtin_amdgcn_s_waitcnt(0);
;         unsigned nloc = b.st[0], nx = b.st[1];
;         if (nloc == 0u) { xcd_barrier_complete(bar, b.x, nloc, nx); b.st[0] = nloc; b.st[1] = nx; }
;         const unsigned old = xb_add(&bar[XB_XSUB(b.x)], 1u);
;         const unsigned gen = old / nloc;
;         if (old + 1u == (gen + 1u) * nloc) {
;             __builtin_amdgcn_fence(__ATOMIC_RELEASE, "agent");
;             asm volatile("s_waitcnt vmcnt(0)" ::: "memory");
;             const unsigned og = xb_add(&bar[XB_TOP], 1u);
;             const unsigned tg = og / nx;
;             if (og + 1u == (tg + 1u) * nx) xb_add(&bar[XB_TOPGEN], 1u);
;             else XB_SPIN(xb_ld(&bar[XB_TOPGEN]) == tg, bar);
;             __builtin_amdgcn_fence(__ATOMIC_ACQUIRE, "agent");
;             xb_add(&bar[XB_XGEN(b.x)], 1u);
;             asm volatile("s_waitcnt vmcnt(0)" ::: "memory");
;         } else {
;             XB_SPIN(xb_ld(&bar[XB_XGEN(b.x)]) == gen, bar);
;             __builtin_amdgcn_fence(__ATOMIC_ACQUIRE, "agent");
;             asm volatile("s_waitcnt vmcnt(0)" ::: "memory");
;         }
;     }
;     __syncthreads();
; }
; __global__ void __launch_bounds__(NTHR, 2) mk_fwd(MkArgs a) {
;     ...
;     SEAM(3);
.Lgb3_poll:
	s_nop 0
	global_load_dword v2, v0, s[90:91] sc1
	s_waitcnt vmcnt(0)
	v_cmp_gt_u32_e32 vcc, 4, v2
	s_cbranch_vccnz .Lgb3_poll
	s_branch .LBB9_497

; __device__ __forceinline__ unsigned xb_ld(unsigned* p)              { return __hip_atomic_load(p, __ATOMIC_RELAXED, __HIP_MEMORY_SCOPE_AGENT); }
; __device__ __forceinline__ unsigned xb_add(unsigned* p, unsigned v) { return __hip_atomic_fetch_add(p, v, __ATOMIC_RELAXED, __HIP_MEMORY_SCOPE_AGENT); }
; #define XB_SPIN(cond, bar) do { unsigned _sp = 0; while (cond) { __builtin_amdgcn_s_sleep(1); \
;     if ((++_sp & 255u) == 0u) { if (xb_ld(&(bar)[XB_TMO])) break; if (_sp > XB_SPIN_CAP) { atomicAdd(&(bar)[XB_TMO], 1u); break; } } } } while (0)
; #define SEAM(k) do { if (IN(k) && IN((k) + 1)) GRID_SYNC(); } while (0)
; __device__ __forceinline__ void xcd_barrier(const XcdBarrier& b) {
;     asm volatile("s_waitcnt vmcnt(0)" ::: "memory");
;     __syncthreads();
;     if (threadIdx.x == 0) {
;         unsigned* bar = b.bar;
;         __builtin_amdgcn_s_waitcnt(0);
;         unsigned nloc = b.st[0], nx = b.st[1];
;         if (nloc == 0u) { xcd_barrier_complete(bar, b.x, nloc, nx); b.st[0] = nloc; b.st[1] = nx; }
;         const unsigned old = xb_add(&bar[XB_XSUB(b.x)], 1u);
;         const unsigned gen = old / nloc;
;         if (old + 1u == (gen + 1u) * nloc) {
;             __builtin_amdgcn_fence(__ATOMIC_RELEASE, "agent");
;             asm volatile("s_waitcnt vmcnt(0)" ::: "memory");
;             const unsigned og = xb_add(&bar[XB_TOP], 1u);
;             const unsigned tg = og / nx;
;             if (og + 1u == (tg + 1u) * nx) xb_add(&bar[XB_TOPGEN], 1u);
;             else XB_SPIN(xb_ld(&bar[XB_TOPGEN]) == tg, bar);
;             __builtin_amdgcn_fence(__ATOMIC_ACQUIRE, "agent");
;             xb_add(&bar[XB_XGEN(b.x)], 1u);
;             asm volatile("s_waitcnt vmcnt(0)" ::: "memory");
;         } else {
;             XB_SPIN(xb_ld(&bar[XB_XGEN(b.x)]) == gen, bar);
;             __builtin_amdgcn_fence(__ATOMIC_ACQUIRE, "agent");
;             asm volatile("s_waitcnt vmcnt(0)" ::: "memory");
;         }
;     }
;     __syncthreads();
; }
; __global__ void __launch_bounds__(NTHR, 2) mk_fwd(MkArgs a) {
;     ...
;     SEAM(5);
.Lgb5_poll:
	s_nop 0
	global_load_dword v2, v0, s[90:91] sc1
	global_load_dword v3, v1, s[90:91] sc1
	s_waitcnt vmcnt(0)
	v_cmp_gt_u32_e32 vcc, 0x400, v2
	s_cbranch_vccnz .Lgb5_poll
	v_cmp_gt_u32_e32 vcc, 0x100, v3
	s_cbranch_vccnz .Lgb5_poll
	s_branch .LBB9_759
